# v17 + C second V-fragment batch reads hoisted above last two PV MFMAs + residual-GEMM row-sum shuffle via permlane32_swap + attention Q-load waits removed
# speedup vs baseline: 1.0117x; 1.0073x over previous
; template <int DQK, int DV, bool BAND>
; DI void attn_unit(const AttnArgs& a, LAS unsigned char* lds, int tid) {
;     ...
;             for (int r = 0; r < 16; ++r) { p0[r] = __builtin_amdgcn_exp2f(p0[r]); p1[r] = __builtin_amdgcn_exp2f(p1[r]); }
;             { u32x4 w;
;               w.x = pk2(p0[0], p0[1]); w.y = pk2(p0[2], p0[3]); w.z = pk2(p0[4], p0[5]); w.w = pk2(p0[6], p0[7]); pa[0] = __builtin_bit_cast(bf16x8, w);
;               w.x = pk2(p0[8], p0[9]); w.y = pk2(p0[10], p0[11]); w.z = pk2(p0[12], p0[13]); w.w = pk2(p0[14], p0[15]); pa[1] = __builtin_bit_cast(bf16x8, w);
;               w.x = pk2(p1[0], p1[1]); w.y = pk2(p1[2], p1[3]); w.z = pk2(p1[4], p1[5]); w.w = pk2(p1[6], p1[7]); pa[2] = __builtin_bit_cast(bf16x8, w);
;               w.x = pk2(p1[8], p1[9]); w.y = pk2(p1[10], p1[11]); w.z = pk2(p1[12], p1[13]); w.w = pk2(p1[14], p1[15]); pa[3] = __builtin_bit_cast(bf16x8, w); }
;             if (DQK > 96) { AT_PV(vcur); } else {
;                 if (!VPRE) { const LAS unsigned char* vp_ = lds + VBUF + vcur + ((lane >> 4) & 1) * 32 + (lane & 3) * 8 + (4 * hi + ((lane & 15) >> 2)) * 64;
; #pragma unroll
;                     for (int d = 0; d < 2; ++d)
; #pragma unroll
;                         for (int ks = 0; ks < 4; ++ks) { vlo[d * 4 + ks] = vtr(vp_ + d * 4096 + ks * 1024); vhi[d * 4 + ks] = vtr(vp_ + d * 4096 + ks * 1024 + 512); }
;                     __builtin_amdgcn_sched_barrier(0); }
; #pragma unroll
;                 for (int ks = 0; ks < 4; ++ks) {
; #pragma unroll
;                     for (int d = 0; d < 2; ++d) { const s16x4 lo = vlo[d * 4 + ks], hh = vhi[d * 4 + ks];
;                         const bf16x8 vf = (bf16x8){lo[0], lo[1], lo[2], lo[3], hh[0], hh[1], hh[2], hh[3]}; o[d] = MFMA32(pa[ks], vf, o[d]); }
;                     lacc = MFMA32(pa[ks], ones, lacc); }
;                 if (NDB > 2) {
;                     const LAS unsigned char* vp_ = lds + VBUF + vcur + ((lane >> 4) & 1) * 32 + (lane & 3) * 8 + (4 * hi + ((lane & 15) >> 2)) * 64;
; #pragma unroll
;                     for (int d = 2; d < NDB; ++d)
; #pragma unroll
;                         for (int ks = 0; ks < 4; ++ks) { vlo[(d - 2) * 4 + ks] = vtr(vp_ + d * 4096 + ks * 1024); vhi[(d - 2) * 4 + ks] = vtr(vp_ + d * 4096 + ks * 1024 + 512); }
;                     __builtin_amdgcn_sched_barrier(0);
; #pragma unroll
;                     for (int ks = 0; ks < 4; ++ks)
.LBB0_227:
	v_exp_f32_e32 v96, v96
	v_exp_f32_e32 v97, v97
	v_exp_f32_e32 v98, v98
	v_exp_f32_e32 v99, v99
	v_exp_f32_e32 v100, v100
	v_exp_f32_e32 v101, v101
	v_exp_f32_e32 v102, v102
	v_exp_f32_e32 v103, v103
	v_exp_f32_e32 v225, v108
	v_exp_f32_e32 v242, v109
	v_exp_f32_e32 v243, v110
	v_exp_f32_e32 v249, v111
	v_cvt_pk_bf16_f32 v108, v96, v97
	v_cvt_pk_bf16_f32 v109, v98, v99
	v_cvt_pk_bf16_f32 v110, v100, v101
	v_cvt_pk_bf16_f32 v111, v102, v103
	v_exp_f32_e32 v104, v104
	v_exp_f32_e32 v105, v105
	v_exp_f32_e32 v106, v106
	v_exp_f32_e32 v107, v107
	s_waitcnt lgkmcnt(14)
	v_mfma_f32_32x32x16_bf16 v[0:15], v[108:111], v[172:175], v[0:15]
	v_add_f32_e32 v64, v64, v104
	v_add_f32_e32 v65, v65, v105
	v_cvt_pk_bf16_f32 v104, v104, v105
	v_exp_f32_e32 v112, v112
	v_add_f32_e32 v64, v64, v106
	v_add_f32_e32 v65, v65, v107
	v_cvt_pk_bf16_f32 v105, v106, v107
	v_cvt_pk_bf16_f32 v106, v225, v242
	v_cvt_pk_bf16_f32 v107, v243, v249
	v_exp_f32_e32 v113, v113
	v_exp_f32_e32 v114, v114
	s_waitcnt lgkmcnt(6)
	v_mfma_f32_32x32x16_bf16 v[48:63], v[108:111], v[168:171], v[48:63]
	v_add_f32_e32 v64, v64, v96
	v_add_f32_e32 v65, v65, v97
	v_add_f32_e32 v64, v64, v98
	v_add_f32_e32 v65, v65, v99
	v_exp_f32_e32 v115, v115
	v_exp_f32_e32 v116, v116
	v_exp_f32_e32 v117, v117
	v_exp_f32_e32 v118, v118
	v_exp_f32_e32 v119, v119
	v_add_f32_e32 v64, v64, v100
	v_add_f32_e32 v65, v65, v101
	v_add_f32_e32 v64, v64, v102
	v_add_f32_e32 v65, v65, v103
	v_cvt_pk_bf16_f32 v100, v112, v113
	v_cvt_pk_bf16_f32 v101, v114, v115
	v_mfma_f32_32x32x16_bf16 v[0:15], v[104:107], v[164:167], v[0:15]
	v_cvt_pk_bf16_f32 v102, v116, v117
	v_cvt_pk_bf16_f32 v103, v118, v119
	v_exp_f32_e32 v120, v120
	v_exp_f32_e32 v121, v121
	v_exp_f32_e32 v122, v122
	v_exp_f32_e32 v123, v123
	v_exp_f32_e32 v124, v124
	v_add_f32_e32 v64, v64, v116
	v_add_f32_e32 v65, v65, v117
	v_add_f32_e32 v64, v64, v118
	v_add_f32_e32 v65, v65, v119
	s_waitcnt lgkmcnt(4)
	v_mfma_f32_32x32x16_bf16 v[48:63], v[104:107], v[160:163], v[48:63]
	v_exp_f32_e32 v125, v125
	v_exp_f32_e32 v126, v126
	v_exp_f32_e32 v127, v127
	v_cvt_pk_bf16_f32 v96, v120, v121
	v_cvt_pk_bf16_f32 v97, v122, v123
	v_mfma_f32_32x32x16_bf16 v[0:15], v[100:103], v[156:159], v[0:15]
	v_cvt_pk_bf16_f32 v98, v124, v125
	v_cvt_pk_bf16_f32 v99, v126, v127
	v_add_f32_e32 v64, v64, v120
	v_add_f32_e32 v65, v65, v121
	v_add_f32_e32 v64, v64, v122
	v_add_f32_e32 v65, v65, v123
	s_waitcnt lgkmcnt(2)
	v_mfma_f32_32x32x16_bf16 v[48:63], v[100:103], v[152:155], v[48:63]
	v_add_f32_e32 v64, v64, v124
	v_add_f32_e32 v65, v65, v125
	v_add_f32_e32 v64, v64, v126
	v_add_f32_e32 v65, v65, v127
	ds_read_b64_tr_b16 v[116:117], v224 offset:57344
	ds_read_b64_tr_b16 v[118:119], v224 offset:57856
	ds_read_b64_tr_b16 v[120:121], v224 offset:58368
	ds_read_b64_tr_b16 v[122:123], v224 offset:58880
	ds_read_b64_tr_b16 v[124:125], v224 offset:59392
	ds_read_b64_tr_b16 v[126:127], v224 offset:59904
	v_mfma_f32_32x32x16_bf16 v[0:15], v[96:99], v[144:147], v[0:15]
	s_waitcnt lgkmcnt(6)
	v_mfma_f32_32x32x16_bf16 v[48:63], v[96:99], v[148:151], v[48:63]
	ds_read_b64_tr_b16 v[144:145], v224 offset:60416
	ds_read_b64_tr_b16 v[146:147], v224 offset:60928
	ds_read_b64_tr_b16 v[148:149], v224 offset:61440
	ds_read_b64_tr_b16 v[150:151], v224 offset:61952
	ds_read_b64_tr_b16 v[152:153], v224 offset:62464
	ds_read_b64_tr_b16 v[154:155], v224 offset:62976
	ds_read_b64_tr_b16 v[156:157], v224 offset:63488
	ds_read_b64_tr_b16 v[158:159], v224 offset:64000
	ds_read_b64_tr_b16 v[160:161], v224 offset:64512
	ds_read_b64_tr_b16 v[162:163], v224 offset:65024
	v_add_f32_e32 v64, v64, v112
	v_add_f32_e32 v65, v65, v113
	v_add_f32_e32 v64, v64, v114
	v_add_f32_e32 v65, v65, v115
	s_waitcnt lgkmcnt(14)
	v_mfma_f32_32x32x16_bf16 v[32:47], v[108:111], v[116:119], v[32:47]
	v_add_f32_e32 v64, v64, v225
	v_add_f32_e32 v65, v65, v242
	v_add_f32_e32 v64, v64, v243
	v_add_f32_e32 v65, v65, v249
	s_add_i32 s34, s34, 1
	s_add_i32 s46, s82, s34
	v_lshl_add_u64 v[190:191], v[190:191], 0, s[74:75]
	v_lshl_add_u64 v[198:199], v[198:199], 0, s[74:75]
	v_lshl_add_u64 v[200:201], v[200:201], 0, s[74:75]
	s_mov_b64 s[40:41], 0
	s_cmp_eq_u32 s46, 2
	s_waitcnt lgkmcnt(6)
	v_mfma_f32_32x32x16_bf16 v[16:31], v[108:111], v[148:151], v[16:31]
	v_mfma_f32_32x32x16_bf16 v[32:47], v[104:107], v[120:123], v[32:47]
	s_waitcnt lgkmcnt(4)
	v_mfma_f32_32x32x16_bf16 v[16:31], v[104:107], v[152:155], v[16:31]
	v_mfma_f32_32x32x16_bf16 v[32:47], v[100:103], v[124:127], v[32:47]
	s_waitcnt lgkmcnt(2)
	v_mfma_f32_32x32x16_bf16 v[16:31], v[100:103], v[156:159], v[16:31]
	v_mfma_f32_32x32x16_bf16 v[32:47], v[96:99], v[144:147], v[32:47]
	s_waitcnt lgkmcnt(0)
	v_mfma_f32_32x32x16_bf16 v[16:31], v[96:99], v[160:163], v[16:31]
	s_cbranch_scc1 .LBB0_207
	s_mov_b32 s48, s35
	s_add_i32 s35, s34, -1
	s_cmp_ge_u32 s35, s69
	s_mov_b64 s[46:47], -1
	s_cbranch_scc1 .LBB0_211
	s_branch .LBB0_212

; #define PG8_GAS __attribute__((address_space(1)))
;     __device__ __forceinline__ void operator()(const f32x4 (&acc)[2][2][4][2], const Unit& u, int wr, int wc, int fr, int fq) const {
;         const int row0 = u.pm * BM + wr * 64 + fr; const int col0 = u.pn * BM + wc * 32 + 8 * fq;
;         PG8_GAS bf16_t* XBg = (PG8_GAS bf16_t*)XB; PG8_GAS unsigned long long* ssg = (PG8_GAS unsigned long long*)ss;
;         u32x4 pre[2][4][2];
; #pragma unroll
;         for (int ai = 0; ai < 2; ++ai)
; #pragma unroll
;             for (int m = 0; m < 4; ++m)
; #pragma unroll
;                 for (int bj = 0; bj < 2; ++bj) pre[ai][m][bj] = *(const PG8_GAS u32x4*)(XBg + (size_t)(row0 + ai * HALF + m * 16) * ldc + col0 + bj * HALF);
; #pragma unroll
;         for (int ai = 0; ai < 2; ++ai)
; #pragma unroll
;             for (int m = 0; m < 4; ++m) { const int row = row0 + ai * HALF + m * 16; PG8_GAS bf16_t* rowb = XBg + (size_t)row * ldc + col0;
;                 float sq = 0.f;
; #pragma unroll
;                 for (int bj = 0; bj < 2; ++bj) { const u32x4 o = pre[ai][m][bj]; const f32x4 c0 = acc[ai][bj][m][0], c1 = acc[ai][bj][m][1];
;                     u32x4 w; w.x = cvt_pk_bf16(__uint_as_float(o.x << 16) + c0[0], __uint_as_float(o.x & 0xffff0000u) + c0[1]); w.y = cvt_pk_bf16(__uint_as_float(o.y << 16) + c0[2], __uint_as_float(o.y & 0xffff0000u) + c0[3]);
;                     w.z = cvt_pk_bf16(__uint_as_float(o.z << 16) + c1[0], __uint_as_float(o.z & 0xffff0000u) + c1[1]); w.w = cvt_pk_bf16(__uint_as_float(o.w << 16) + c1[2], __uint_as_float(o.w & 0xffff0000u) + c1[3]);
;                     *(PG8_GAS u32x4*)(rowb + bj * HALF) = w;
;                     const float a0 = __uint_as_float(w.x << 16), a1 = __uint_as_float(w.x & 0xffff0000u), a2 = __uint_as_float(w.y << 16), a3 = __uint_as_float(w.y & 0xffff0000u);
;                     const float b0 = __uint_as_float(w.z << 16), b1 = __uint_as_float(w.z & 0xffff0000u), b2 = __uint_as_float(w.w << 16), b3 = __uint_as_float(w.w & 0xffff0000u);
;                     sq += (a0 * a0 + a1 * a1) + (a2 * a2 + a3 * a3) + (b0 * b0 + b1 * b1) + (b2 * b2 + b3 * b3); }
;                 sq += __shfl_xor(sq, 16); sq += __shfl_xor(sq, 32);
;                 if (fq == 0) __hip_atomic_fetch_add(ssg + row, (unsigned long long)(sq * 1048576.0f + 0.5f), __ATOMIC_RELAXED, __HIP_MEMORY_SCOPE_AGENT); }
.LBB0_383:
	v_lshl_add_u32 v222, s76, 8, v196
	v_lshl_or_b32 v124, s57, 8, v250
	v_ashrrev_i32_e32 v125, 31, v124
	v_ashrrev_i32_e32 v223, 31, v222
	v_lshl_add_u64 v[124:125], v[124:125], 1, s[14:15]
	v_lshlrev_b64 v[126:127], 11, v[222:223]
	v_lshl_add_u64 v[224:225], v[124:125], 0, v[126:127]
	global_load_dwordx4 v[188:191], v[224:225], off
	global_load_dwordx4 v[184:187], v[224:225], off offset:256
	v_or_b32_e32 v126, 16, v222
	v_ashrrev_i32_e32 v127, 31, v126
	v_lshlrev_b64 v[126:127], 11, v[126:127]
	v_lshl_add_u64 v[220:221], v[124:125], 0, v[126:127]
	v_or_b32_e32 v126, 32, v222
	v_ashrrev_i32_e32 v127, 31, v126
	v_lshlrev_b64 v[126:127], 11, v[126:127]
	v_lshl_add_u64 v[218:219], v[124:125], 0, v[126:127]
	v_or_b32_e32 v126, 48, v222
	v_ashrrev_i32_e32 v127, 31, v126
	s_mov_b64 s[40:41], 0x40000
	v_lshlrev_b64 v[126:127], 11, v[126:127]
	v_lshl_add_u64 v[214:215], v[224:225], 0, s[40:41]
	s_mov_b32 s40, 0x40000
	v_lshl_add_u64 v[216:217], v[124:125], 0, v[126:127]
	v_add_co_u32_e32 v124, vcc, s40, v224
	s_mov_b64 s[40:41], 0x48000
	s_nop 0
	v_addc_co_u32_e32 v125, vcc, 0, v225, vcc
	v_lshl_add_u64 v[212:213], v[224:225], 0, s[40:41]
	s_mov_b32 s40, 0x48000
	global_load_dwordx4 v[180:183], v[220:221], off
	global_load_dwordx4 v[176:179], v[220:221], off offset:256
	global_load_dwordx4 v[172:175], v[218:219], off
	global_load_dwordx4 v[168:171], v[218:219], off offset:256
	global_load_dwordx4 v[164:167], v[216:217], off
	global_load_dwordx4 v[156:159], v[216:217], off offset:256
	global_load_dwordx4 v[160:163], v[124:125], off
	global_load_dwordx4 v[152:155], v[214:215], off offset:256
	v_add_co_u32_e32 v124, vcc, s40, v224
	s_mov_b64 s[40:41], 0x50000
	s_nop 0
	v_addc_co_u32_e32 v125, vcc, 0, v225, vcc
	v_lshl_add_u64 v[210:211], v[224:225], 0, s[40:41]
	s_mov_b32 s40, 0x50000
	global_load_dwordx4 v[148:151], v[124:125], off
	global_load_dwordx4 v[144:147], v[212:213], off offset:256
	v_add_co_u32_e32 v124, vcc, s40, v224
	s_mov_b64 s[40:41], 0x58000
	s_nop 0
	v_addc_co_u32_e32 v125, vcc, 0, v225, vcc
	v_lshl_add_u64 v[208:209], v[224:225], 0, s[40:41]
	s_mov_b32 s40, 0x58000
	global_load_dwordx4 v[140:143], v[124:125], off
	global_load_dwordx4 v[128:131], v[210:211], off offset:256
	v_add_co_u32_e32 v124, vcc, s40, v224
	s_waitcnt vmcnt(0)
	v_lshlrev_b32_e32 v242, 16, v188
	v_addc_co_u32_e32 v125, vcc, 0, v225, vcc
	global_load_dwordx4 v[132:135], v[124:125], off
	s_nop 0
	global_load_dwordx4 v[124:127], v[208:209], off offset:256
	v_and_b32_e32 v188, 0xffff0000, v188
	v_add_f32_e32 v136, v136, v242
	v_add_f32_e32 v137, v137, v188
	v_cvt_pk_bf16_f32 v136, v136, v137
	v_lshlrev_b32_e32 v137, 16, v189
	v_add_f32_e32 v137, v138, v137
	v_and_b32_e32 v138, 0xffff0000, v189
	v_add_f32_e32 v138, v139, v138
	v_cvt_pk_bf16_f32 v137, v137, v138
	v_lshlrev_b32_e32 v138, 16, v190
	v_add_f32_e32 v120, v120, v138
	v_and_b32_e32 v138, 0xffff0000, v190
	v_add_f32_e32 v121, v121, v138
	v_cvt_pk_bf16_f32 v138, v120, v121
	v_and_b32_e32 v121, 0xffff0000, v191
	v_lshlrev_b32_e32 v120, 16, v191
	v_add_f32_e32 v121, v123, v121
	v_add_f32_e32 v120, v122, v120
	v_cvt_pk_bf16_f32 v139, v120, v121
	v_and_b32_e32 v121, 0xffff0000, v136
	v_lshlrev_b32_e32 v120, 16, v136
	v_and_b32_e32 v123, 0xffff0000, v137
	v_mul_f32_e32 v121, v121, v121
	v_lshlrev_b32_e32 v122, 16, v137
	v_fmac_f32_e32 v121, v120, v120
	v_mul_f32_e32 v120, v123, v123
	global_store_dwordx4 v[224:225], v[136:139], off
	v_fmac_f32_e32 v120, v122, v122
	v_add_f32_e32 v120, v121, v120
	v_and_b32_e32 v137, 0xffff0000, v138
	v_lshlrev_b32_e32 v136, 16, v138
	v_mul_f32_e32 v121, v137, v137
	v_lshlrev_b32_e32 v138, 16, v139
	v_and_b32_e32 v139, 0xffff0000, v139
	v_fmac_f32_e32 v121, v136, v136
	v_add_f32_e32 v120, v120, v121
	v_mul_f32_e32 v121, v139, v139
	v_fmac_f32_e32 v121, v138, v138
	v_add_f32_e32 v120, v120, v121
	v_lshlrev_b32_e32 v121, 16, v184
	v_add_f32_e32 v116, v116, v121
	v_and_b32_e32 v121, 0xffff0000, v184
	v_add_f32_e32 v117, v117, v121
	v_cvt_pk_bf16_f32 v116, v116, v117
	v_lshlrev_b32_e32 v117, 16, v185
	v_add_f32_e32 v117, v118, v117
	v_and_b32_e32 v118, 0xffff0000, v185
	v_add_f32_e32 v118, v119, v118
	v_cvt_pk_bf16_f32 v117, v117, v118
	v_lshlrev_b32_e32 v118, 16, v186
	v_add_f32_e32 v112, v112, v118
	v_and_b32_e32 v118, 0xffff0000, v186
	v_add_f32_e32 v113, v113, v118
	v_cvt_pk_bf16_f32 v118, v112, v113
	v_and_b32_e32 v113, 0xffff0000, v187
	v_lshlrev_b32_e32 v112, 16, v187
	v_add_f32_e32 v113, v115, v113
	v_add_f32_e32 v112, v114, v112
	v_cvt_pk_bf16_f32 v119, v112, v113
	v_and_b32_e32 v113, 0xffff0000, v116
	v_lshlrev_b32_e32 v112, 16, v116
	v_and_b32_e32 v115, 0xffff0000, v117
	v_mul_f32_e32 v113, v113, v113
	v_lshlrev_b32_e32 v114, 16, v117
	v_fmac_f32_e32 v113, v112, v112
	v_mul_f32_e32 v112, v115, v115
	global_store_dwordx4 v[224:225], v[116:119], off offset:256
	v_fmac_f32_e32 v112, v114, v114
	v_add_f32_e32 v112, v113, v112
	v_and_b32_e32 v117, 0xffff0000, v118
	v_lshlrev_b32_e32 v116, 16, v118
	v_mul_f32_e32 v113, v117, v117
	v_lshlrev_b32_e32 v118, 16, v119
	v_and_b32_e32 v119, 0xffff0000, v119
	v_fmac_f32_e32 v113, v116, v116
	v_add_f32_e32 v112, v112, v113
	v_mul_f32_e32 v113, v119, v119
	v_fmac_f32_e32 v113, v118, v118
	v_cmp_lt_i32_e32 vcc, v245, v240
	v_add_f32_e32 v112, v112, v113
	v_add_f32_e32 v112, v120, v112
	v_cndmask_b32_e32 v113, v239, v245, vcc
	v_lshlrev_b32_e32 v114, 2, v113
	ds_bpermute_b32 v113, v114, v112
	v_cmp_lt_i32_e32 vcc, v246, v240
	s_waitcnt lgkmcnt(0)
	v_add_f32_e32 v116, v112, v113
	v_cndmask_b32_e32 v112, v239, v246, vcc
	v_lshlrev_b32_e32 v115, 2, v112
	v_mov_b32_e32 v117, v116
	s_nop 1
	v_permlane32_swap_b32_e32 v117, v116
	v_lshl_add_u64 v[112:113], v[222:223], 3, s[54:55]
	s_and_saveexec_b64 s[40:41], s[38:39]
	s_cbranch_execz .LBB0_385
	s_waitcnt lgkmcnt(0)
	v_add_f32_e32 v116, v116, v117
	v_fma_f32 v116, v116, s80, 0.5
	v_trunc_f32_e32 v116, v116
	v_mul_f32_e32 v117, 0x2f800000, v116
	v_floor_f32_e32 v117, v117
	v_fmac_f32_e32 v116, 0xcf800000, v117
	v_cvt_u32_f32_e32 v116, v116
	v_cvt_u32_f32_e32 v117, v117
	global_atomic_add_x2 v[112:113], v[116:117], off
; #define PG8_GAS __attribute__((address_space(1)))
; __device__ __forceinline__ unsigned cvt_pk_bf16(float lo, float hi) { unsigned r; asm volatile("v_cvt_pk_bf16_f32 %0, %1, %2" : "=v"(r) : "v"(lo), "v"(hi)); return r; }
;     __device__ __forceinline__ void operator()(const f32x4 (&acc)[2][2][4][2], const Unit& u, int wr, int wc, int fr, int fq) const {
;     ...
;             for (int m = 0; m < 4; ++m) { const int row = row0 + ai * HALF + m * 16; PG8_GAS bf16_t* rowb = XBg + (size_t)row * ldc + col0;
;                 float sq = 0.f;
; #pragma unroll
;                 for (int bj = 0; bj < 2; ++bj) { const u32x4 o = pre[ai][m][bj]; const f32x4 c0 = acc[ai][bj][m][0], c1 = acc[ai][bj][m][1];
;                     u32x4 w; w.x = cvt_pk_bf16(__uint_as_float(o.x << 16) + c0[0], __uint_as_float(o.x & 0xffff0000u) + c0[1]); w.y = cvt_pk_bf16(__uint_as_float(o.y << 16) + c0[2], __uint_as_float(o.y & 0xffff0000u) + c0[3]);
;                     w.z = cvt_pk_bf16(__uint_as_float(o.z << 16) + c1[0], __uint_as_float(o.z & 0xffff0000u) + c1[1]); w.w = cvt_pk_bf16(__uint_as_float(o.w << 16) + c1[2], __uint_as_float(o.w & 0xffff0000u) + c1[3]);
;                     *(PG8_GAS u32x4*)(rowb + bj * HALF) = w;
;                     const float a0 = __uint_as_float(w.x << 16), a1 = __uint_as_float(w.x & 0xffff0000u), a2 = __uint_as_float(w.y << 16), a3 = __uint_as_float(w.y & 0xffff0000u);
;                     const float b0 = __uint_as_float(w.z << 16), b1 = __uint_as_float(w.z & 0xffff0000u), b2 = __uint_as_float(w.w << 16), b3 = __uint_as_float(w.w & 0xffff0000u);
;                     sq += (a0 * a0 + a1 * a1) + (a2 * a2 + a3 * a3) + (b0 * b0 + b1 * b1) + (b2 * b2 + b3 * b3); }
;                 sq += __shfl_xor(sq, 16); sq += __shfl_xor(sq, 32);
;                 if (fq == 0) __hip_atomic_fetch_add(ssg + row, (unsigned long long)(sq * 1048576.0f + 0.5f), __ATOMIC_RELAXED, __HIP_MEMORY_SCOPE_AGENT); }
.LBB0_385:
	s_or_b64 exec, exec, s[40:41]
	v_lshlrev_b32_e32 v116, 16, v180
	v_add_f32_e32 v108, v108, v116
	v_and_b32_e32 v116, 0xffff0000, v180
	v_add_f32_e32 v109, v109, v116
	v_cvt_pk_bf16_f32 v108, v108, v109
	v_lshlrev_b32_e32 v109, 16, v181
	v_add_f32_e32 v109, v110, v109
	v_and_b32_e32 v110, 0xffff0000, v181
	v_add_f32_e32 v110, v111, v110
	v_cvt_pk_bf16_f32 v109, v109, v110
	v_lshlrev_b32_e32 v110, 16, v182
	v_add_f32_e32 v104, v104, v110
	v_and_b32_e32 v110, 0xffff0000, v182
	v_add_f32_e32 v105, v105, v110
	v_cvt_pk_bf16_f32 v110, v104, v105
	v_and_b32_e32 v105, 0xffff0000, v183
	v_lshlrev_b32_e32 v104, 16, v183
	v_add_f32_e32 v105, v107, v105
	v_add_f32_e32 v104, v106, v104
	v_cvt_pk_bf16_f32 v111, v104, v105
	v_and_b32_e32 v105, 0xffff0000, v108
	v_lshlrev_b32_e32 v104, 16, v108
	v_and_b32_e32 v107, 0xffff0000, v109
	v_mul_f32_e32 v105, v105, v105
	v_lshlrev_b32_e32 v106, 16, v109
	v_fmac_f32_e32 v105, v104, v104
	v_mul_f32_e32 v104, v107, v107
	global_store_dwordx4 v[220:221], v[108:111], off
	v_fmac_f32_e32 v104, v106, v106
	v_add_f32_e32 v104, v105, v104
	v_and_b32_e32 v109, 0xffff0000, v110
	v_lshlrev_b32_e32 v108, 16, v110
	v_mul_f32_e32 v105, v109, v109
	v_lshlrev_b32_e32 v110, 16, v111
	v_and_b32_e32 v111, 0xffff0000, v111
	v_fmac_f32_e32 v105, v108, v108
	v_add_f32_e32 v104, v104, v105
	v_mul_f32_e32 v105, v111, v111
	v_fmac_f32_e32 v105, v110, v110
	v_add_f32_e32 v104, v104, v105
	v_lshlrev_b32_e32 v105, 16, v176
	v_add_f32_e32 v100, v100, v105
	v_and_b32_e32 v105, 0xffff0000, v176
	v_add_f32_e32 v101, v101, v105
	v_cvt_pk_bf16_f32 v100, v100, v101
	v_lshlrev_b32_e32 v101, 16, v177
	v_add_f32_e32 v101, v102, v101
	v_and_b32_e32 v102, 0xffff0000, v177
	v_add_f32_e32 v102, v103, v102
	v_cvt_pk_bf16_f32 v101, v101, v102
	v_lshlrev_b32_e32 v102, 16, v178
	v_add_f32_e32 v96, v96, v102
	v_and_b32_e32 v102, 0xffff0000, v178
	v_add_f32_e32 v97, v97, v102
	v_cvt_pk_bf16_f32 v102, v96, v97
	v_and_b32_e32 v97, 0xffff0000, v179
	v_lshlrev_b32_e32 v96, 16, v179
	v_add_f32_e32 v97, v99, v97
	v_add_f32_e32 v96, v98, v96
	v_cvt_pk_bf16_f32 v103, v96, v97
	v_and_b32_e32 v97, 0xffff0000, v100
	v_lshlrev_b32_e32 v96, 16, v100
	v_and_b32_e32 v99, 0xffff0000, v101
	v_mul_f32_e32 v97, v97, v97
	v_lshlrev_b32_e32 v98, 16, v101
	v_fmac_f32_e32 v97, v96, v96
	v_mul_f32_e32 v96, v99, v99
	v_and_b32_e32 v106, 0xffff0000, v102
	v_fmac_f32_e32 v96, v98, v98
	v_lshlrev_b32_e32 v105, 16, v102
	v_add_f32_e32 v96, v97, v96
	v_mul_f32_e32 v97, v106, v106
	v_and_b32_e32 v108, 0xffff0000, v103
	v_fmac_f32_e32 v97, v105, v105
	v_lshlrev_b32_e32 v107, 16, v103
	v_add_f32_e32 v96, v96, v97
	v_mul_f32_e32 v97, v108, v108
	v_fmac_f32_e32 v97, v107, v107
	v_add_f32_e32 v96, v96, v97
	v_add_f32_e32 v96, v104, v96
	ds_bpermute_b32 v97, v114, v96
	global_store_dwordx4 v[220:221], v[100:103], off offset:256
	s_waitcnt lgkmcnt(0)
	v_add_f32_e32 v96, v96, v97
	v_mov_b32_e32 v97, v96
	s_nop 1
	v_permlane32_swap_b32_e32 v97, v96
	s_and_saveexec_b64 s[40:41], s[38:39]
	s_cbranch_execz .LBB0_387
	s_waitcnt lgkmcnt(0)
	v_add_f32_e32 v96, v96, v97
	v_fma_f32 v96, v96, s80, 0.5
	v_trunc_f32_e32 v96, v96
	v_mul_f32_e32 v97, 0x2f800000, v96
	v_floor_f32_e32 v97, v97
	v_fmac_f32_e32 v96, 0xcf800000, v97
	v_cvt_u32_f32_e32 v96, v96
	v_cvt_u32_f32_e32 v97, v97
	global_atomic_add_x2 v[112:113], v[96:97], off offset:128
.LBB0_387:
	s_or_b64 exec, exec, s[40:41]
	v_lshlrev_b32_e32 v96, 16, v172
	v_add_f32_e32 v92, v92, v96
	v_and_b32_e32 v96, 0xffff0000, v172
	v_add_f32_e32 v93, v93, v96
	v_cvt_pk_bf16_f32 v92, v92, v93
	v_lshlrev_b32_e32 v93, 16, v173
	v_add_f32_e32 v93, v94, v93
	v_and_b32_e32 v94, 0xffff0000, v173
	v_add_f32_e32 v94, v95, v94
	v_cvt_pk_bf16_f32 v93, v93, v94
	v_lshlrev_b32_e32 v94, 16, v174
	v_add_f32_e32 v88, v88, v94
	v_and_b32_e32 v94, 0xffff0000, v174
	v_add_f32_e32 v89, v89, v94
	v_cvt_pk_bf16_f32 v94, v88, v89
	v_and_b32_e32 v89, 0xffff0000, v175
	v_lshlrev_b32_e32 v88, 16, v175
	v_add_f32_e32 v89, v91, v89
	v_add_f32_e32 v88, v90, v88
	v_cvt_pk_bf16_f32 v95, v88, v89
	v_and_b32_e32 v89, 0xffff0000, v92
	v_lshlrev_b32_e32 v88, 16, v92
	v_and_b32_e32 v91, 0xffff0000, v93
	v_mul_f32_e32 v89, v89, v89
	v_lshlrev_b32_e32 v90, 16, v93
	v_fmac_f32_e32 v89, v88, v88
	v_mul_f32_e32 v88, v91, v91
	global_store_dwordx4 v[218:219], v[92:95], off
	v_fmac_f32_e32 v88, v90, v90
	v_add_f32_e32 v88, v89, v88
	v_and_b32_e32 v93, 0xffff0000, v94
	v_lshlrev_b32_e32 v92, 16, v94
	v_mul_f32_e32 v89, v93, v93
	v_lshlrev_b32_e32 v94, 16, v95
	v_and_b32_e32 v95, 0xffff0000, v95
	v_fmac_f32_e32 v89, v92, v92
	v_add_f32_e32 v88, v88, v89
	v_mul_f32_e32 v89, v95, v95
	v_fmac_f32_e32 v89, v94, v94
	v_add_f32_e32 v88, v88, v89
	v_lshlrev_b32_e32 v89, 16, v168
	v_add_f32_e32 v84, v84, v89
	v_and_b32_e32 v89, 0xffff0000, v168
	v_add_f32_e32 v85, v85, v89
	v_cvt_pk_bf16_f32 v84, v84, v85
	v_lshlrev_b32_e32 v85, 16, v169
	v_add_f32_e32 v85, v86, v85
	v_and_b32_e32 v86, 0xffff0000, v169
	v_add_f32_e32 v86, v87, v86
	v_cvt_pk_bf16_f32 v85, v85, v86
	v_lshlrev_b32_e32 v86, 16, v170
	v_add_f32_e32 v80, v80, v86
	v_and_b32_e32 v86, 0xffff0000, v170
	v_add_f32_e32 v81, v81, v86
	v_cvt_pk_bf16_f32 v86, v80, v81
	v_and_b32_e32 v81, 0xffff0000, v171
	v_lshlrev_b32_e32 v80, 16, v171
	v_add_f32_e32 v81, v83, v81
	v_add_f32_e32 v80, v82, v80
	v_cvt_pk_bf16_f32 v87, v80, v81
	v_and_b32_e32 v81, 0xffff0000, v84
	v_lshlrev_b32_e32 v80, 16, v84
	v_and_b32_e32 v83, 0xffff0000, v85
	v_mul_f32_e32 v81, v81, v81
	v_lshlrev_b32_e32 v82, 16, v85
	v_fmac_f32_e32 v81, v80, v80
	v_mul_f32_e32 v80, v83, v83
	v_and_b32_e32 v90, 0xffff0000, v86
	v_fmac_f32_e32 v80, v82, v82
	v_lshlrev_b32_e32 v89, 16, v86
	v_add_f32_e32 v80, v81, v80
	v_mul_f32_e32 v81, v90, v90
	v_and_b32_e32 v92, 0xffff0000, v87
	v_fmac_f32_e32 v81, v89, v89
	v_lshlrev_b32_e32 v91, 16, v87
	v_add_f32_e32 v80, v80, v81
	v_mul_f32_e32 v81, v92, v92
	v_fmac_f32_e32 v81, v91, v91
	v_add_f32_e32 v80, v80, v81
	v_add_f32_e32 v80, v88, v80
	ds_bpermute_b32 v81, v114, v80
	global_store_dwordx4 v[218:219], v[84:87], off offset:256
	s_waitcnt lgkmcnt(0)
	v_add_f32_e32 v80, v80, v81
	v_mov_b32_e32 v81, v80
	s_nop 1
	v_permlane32_swap_b32_e32 v81, v80
	s_and_saveexec_b64 s[40:41], s[38:39]
	s_cbranch_execz .LBB0_389
	s_waitcnt lgkmcnt(0)
	v_add_f32_e32 v80, v80, v81
	v_fma_f32 v80, v80, s80, 0.5
	v_trunc_f32_e32 v80, v80
	v_mul_f32_e32 v81, 0x2f800000, v80
	v_floor_f32_e32 v81, v81
	v_fmac_f32_e32 v80, 0xcf800000, v81
	v_cvt_u32_f32_e32 v80, v80
	v_cvt_u32_f32_e32 v81, v81
	global_atomic_add_x2 v[112:113], v[80:81], off offset:256
; #define PG8_GAS __attribute__((address_space(1)))
; __device__ __forceinline__ unsigned cvt_pk_bf16(float lo, float hi) { unsigned r; asm volatile("v_cvt_pk_bf16_f32 %0, %1, %2" : "=v"(r) : "v"(lo), "v"(hi)); return r; }
;     __device__ __forceinline__ void operator()(const f32x4 (&acc)[2][2][4][2], const Unit& u, int wr, int wc, int fr, int fq) const {
;     ...
;             for (int m = 0; m < 4; ++m) { const int row = row0 + ai * HALF + m * 16; PG8_GAS bf16_t* rowb = XBg + (size_t)row * ldc + col0;
;                 float sq = 0.f;
; #pragma unroll
;                 for (int bj = 0; bj < 2; ++bj) { const u32x4 o = pre[ai][m][bj]; const f32x4 c0 = acc[ai][bj][m][0], c1 = acc[ai][bj][m][1];
;                     u32x4 w; w.x = cvt_pk_bf16(__uint_as_float(o.x << 16) + c0[0], __uint_as_float(o.x & 0xffff0000u) + c0[1]); w.y = cvt_pk_bf16(__uint_as_float(o.y << 16) + c0[2], __uint_as_float(o.y & 0xffff0000u) + c0[3]);
;                     w.z = cvt_pk_bf16(__uint_as_float(o.z << 16) + c1[0], __uint_as_float(o.z & 0xffff0000u) + c1[1]); w.w = cvt_pk_bf16(__uint_as_float(o.w << 16) + c1[2], __uint_as_float(o.w & 0xffff0000u) + c1[3]);
;                     *(PG8_GAS u32x4*)(rowb + bj * HALF) = w;
;                     const float a0 = __uint_as_float(w.x << 16), a1 = __uint_as_float(w.x & 0xffff0000u), a2 = __uint_as_float(w.y << 16), a3 = __uint_as_float(w.y & 0xffff0000u);
;                     const float b0 = __uint_as_float(w.z << 16), b1 = __uint_as_float(w.z & 0xffff0000u), b2 = __uint_as_float(w.w << 16), b3 = __uint_as_float(w.w & 0xffff0000u);
;                     sq += (a0 * a0 + a1 * a1) + (a2 * a2 + a3 * a3) + (b0 * b0 + b1 * b1) + (b2 * b2 + b3 * b3); }
;                 sq += __shfl_xor(sq, 16); sq += __shfl_xor(sq, 32);
;                 if (fq == 0) __hip_atomic_fetch_add(ssg + row, (unsigned long long)(sq * 1048576.0f + 0.5f), __ATOMIC_RELAXED, __HIP_MEMORY_SCOPE_AGENT); }
.LBB0_389:
	s_or_b64 exec, exec, s[40:41]
	v_lshlrev_b32_e32 v80, 16, v164
	v_add_f32_e32 v76, v76, v80
	v_and_b32_e32 v80, 0xffff0000, v164
	v_add_f32_e32 v77, v77, v80
	v_cvt_pk_bf16_f32 v76, v76, v77
	v_lshlrev_b32_e32 v77, 16, v165
	v_add_f32_e32 v77, v78, v77
	v_and_b32_e32 v78, 0xffff0000, v165
	v_add_f32_e32 v78, v79, v78
	v_cvt_pk_bf16_f32 v77, v77, v78
	v_lshlrev_b32_e32 v78, 16, v166
	v_add_f32_e32 v72, v72, v78
	v_and_b32_e32 v78, 0xffff0000, v166
	v_add_f32_e32 v73, v73, v78
	v_cvt_pk_bf16_f32 v78, v72, v73
	v_and_b32_e32 v73, 0xffff0000, v167
	v_lshlrev_b32_e32 v72, 16, v167
	v_add_f32_e32 v73, v75, v73
	v_add_f32_e32 v72, v74, v72
	v_cvt_pk_bf16_f32 v79, v72, v73
	v_and_b32_e32 v73, 0xffff0000, v76
	v_lshlrev_b32_e32 v72, 16, v76
	v_and_b32_e32 v75, 0xffff0000, v77
	v_mul_f32_e32 v73, v73, v73
	v_lshlrev_b32_e32 v74, 16, v77
	v_fmac_f32_e32 v73, v72, v72
	v_mul_f32_e32 v72, v75, v75
	global_store_dwordx4 v[216:217], v[76:79], off
	v_fmac_f32_e32 v72, v74, v74
	v_add_f32_e32 v72, v73, v72
	v_and_b32_e32 v77, 0xffff0000, v78
	v_lshlrev_b32_e32 v76, 16, v78
	v_mul_f32_e32 v73, v77, v77
	v_lshlrev_b32_e32 v78, 16, v79
	v_and_b32_e32 v79, 0xffff0000, v79
	v_fmac_f32_e32 v73, v76, v76
	v_add_f32_e32 v72, v72, v73
	v_mul_f32_e32 v73, v79, v79
	v_fmac_f32_e32 v73, v78, v78
	v_add_f32_e32 v72, v72, v73
	v_lshlrev_b32_e32 v73, 16, v156
	v_add_f32_e32 v68, v68, v73
	v_and_b32_e32 v73, 0xffff0000, v156
	v_add_f32_e32 v69, v69, v73
	v_cvt_pk_bf16_f32 v68, v68, v69
	v_lshlrev_b32_e32 v69, 16, v157
	v_add_f32_e32 v69, v70, v69
	v_and_b32_e32 v70, 0xffff0000, v157
	v_add_f32_e32 v70, v71, v70
	v_cvt_pk_bf16_f32 v69, v69, v70
	v_lshlrev_b32_e32 v70, 16, v158
	v_add_f32_e32 v64, v64, v70
	v_and_b32_e32 v70, 0xffff0000, v158
	v_add_f32_e32 v65, v65, v70
	v_cvt_pk_bf16_f32 v70, v64, v65
	v_and_b32_e32 v65, 0xffff0000, v159
	v_lshlrev_b32_e32 v64, 16, v159
	v_add_f32_e32 v65, v67, v65
	v_add_f32_e32 v64, v66, v64
	v_cvt_pk_bf16_f32 v71, v64, v65
	v_and_b32_e32 v65, 0xffff0000, v68
	v_lshlrev_b32_e32 v64, 16, v68
	v_and_b32_e32 v67, 0xffff0000, v69
	v_mul_f32_e32 v65, v65, v65
	v_lshlrev_b32_e32 v66, 16, v69
	v_fmac_f32_e32 v65, v64, v64
	v_mul_f32_e32 v64, v67, v67
	v_and_b32_e32 v74, 0xffff0000, v70
	v_fmac_f32_e32 v64, v66, v66
	v_lshlrev_b32_e32 v73, 16, v70
	v_add_f32_e32 v64, v65, v64
	v_mul_f32_e32 v65, v74, v74
	v_and_b32_e32 v76, 0xffff0000, v71
	v_fmac_f32_e32 v65, v73, v73
	v_lshlrev_b32_e32 v75, 16, v71
	v_add_f32_e32 v64, v64, v65
	v_mul_f32_e32 v65, v76, v76
	v_fmac_f32_e32 v65, v75, v75
	v_add_f32_e32 v64, v64, v65
	v_add_f32_e32 v64, v72, v64
	ds_bpermute_b32 v65, v114, v64
	global_store_dwordx4 v[216:217], v[68:71], off offset:256
	s_waitcnt lgkmcnt(0)
	v_add_f32_e32 v64, v64, v65
	v_mov_b32_e32 v65, v64
	s_nop 1
	v_permlane32_swap_b32_e32 v65, v64
	s_and_saveexec_b64 s[40:41], s[38:39]
	s_cbranch_execz .LBB0_391
	s_waitcnt lgkmcnt(0)
	v_add_f32_e32 v64, v64, v65
	v_fma_f32 v64, v64, s80, 0.5
	v_trunc_f32_e32 v64, v64
	v_mul_f32_e32 v65, 0x2f800000, v64
	v_floor_f32_e32 v65, v65
	v_fmac_f32_e32 v64, 0xcf800000, v65
	v_cvt_u32_f32_e32 v64, v64
	v_cvt_u32_f32_e32 v65, v65
	global_atomic_add_x2 v[112:113], v[64:65], off offset:384
.LBB0_391:
	s_or_b64 exec, exec, s[40:41]
	v_lshlrev_b32_e32 v64, 16, v160
	v_add_f32_e32 v60, v60, v64
	v_and_b32_e32 v64, 0xffff0000, v160
	v_add_f32_e32 v61, v61, v64
	v_cvt_pk_bf16_f32 v60, v60, v61
	v_lshlrev_b32_e32 v61, 16, v161
	v_add_f32_e32 v61, v62, v61
	v_and_b32_e32 v62, 0xffff0000, v161
	v_add_f32_e32 v62, v63, v62
	v_cvt_pk_bf16_f32 v61, v61, v62
	v_lshlrev_b32_e32 v62, 16, v162
	v_add_f32_e32 v56, v56, v62
	v_and_b32_e32 v62, 0xffff0000, v162
	v_add_f32_e32 v57, v57, v62
	v_cvt_pk_bf16_f32 v62, v56, v57
	v_and_b32_e32 v57, 0xffff0000, v163
	v_lshlrev_b32_e32 v56, 16, v163
	v_add_f32_e32 v57, v59, v57
	v_add_f32_e32 v56, v58, v56
	v_cvt_pk_bf16_f32 v63, v56, v57
	v_and_b32_e32 v57, 0xffff0000, v60
	v_lshlrev_b32_e32 v56, 16, v60
	v_and_b32_e32 v59, 0xffff0000, v61
	v_mul_f32_e32 v57, v57, v57
	v_lshlrev_b32_e32 v58, 16, v61
	v_fmac_f32_e32 v57, v56, v56
	v_mul_f32_e32 v56, v59, v59
	global_store_dwordx4 v[214:215], v[60:63], off
	v_fmac_f32_e32 v56, v58, v58
	v_add_f32_e32 v56, v57, v56
	v_and_b32_e32 v61, 0xffff0000, v62
	v_lshlrev_b32_e32 v60, 16, v62
	v_mul_f32_e32 v57, v61, v61
	v_lshlrev_b32_e32 v62, 16, v63
	v_and_b32_e32 v63, 0xffff0000, v63
	v_fmac_f32_e32 v57, v60, v60
	v_add_f32_e32 v56, v56, v57
	v_mul_f32_e32 v57, v63, v63
	v_fmac_f32_e32 v57, v62, v62
	v_add_f32_e32 v56, v56, v57
	v_lshlrev_b32_e32 v57, 16, v152
	v_add_f32_e32 v52, v52, v57
	v_and_b32_e32 v57, 0xffff0000, v152
	v_add_f32_e32 v53, v53, v57
	v_cvt_pk_bf16_f32 v52, v52, v53
	v_lshlrev_b32_e32 v53, 16, v153
	v_add_f32_e32 v53, v54, v53
	v_and_b32_e32 v54, 0xffff0000, v153
	v_add_f32_e32 v54, v55, v54
	v_cvt_pk_bf16_f32 v53, v53, v54
	v_lshlrev_b32_e32 v54, 16, v154
	v_add_f32_e32 v48, v48, v54
	v_and_b32_e32 v54, 0xffff0000, v154
	v_add_f32_e32 v49, v49, v54
	v_cvt_pk_bf16_f32 v54, v48, v49
	v_and_b32_e32 v49, 0xffff0000, v155
	v_lshlrev_b32_e32 v48, 16, v155
	v_add_f32_e32 v49, v51, v49
	v_add_f32_e32 v48, v50, v48
	v_cvt_pk_bf16_f32 v55, v48, v49
	v_and_b32_e32 v49, 0xffff0000, v52
	v_lshlrev_b32_e32 v48, 16, v52
	v_and_b32_e32 v51, 0xffff0000, v53
	v_mul_f32_e32 v49, v49, v49
	v_lshlrev_b32_e32 v50, 16, v53
	v_fmac_f32_e32 v49, v48, v48
	v_mul_f32_e32 v48, v51, v51
	v_and_b32_e32 v58, 0xffff0000, v54
	v_fmac_f32_e32 v48, v50, v50
	v_lshlrev_b32_e32 v57, 16, v54
	v_add_f32_e32 v48, v49, v48
	v_mul_f32_e32 v49, v58, v58
	v_and_b32_e32 v60, 0xffff0000, v55
	v_fmac_f32_e32 v49, v57, v57
	v_lshlrev_b32_e32 v59, 16, v55
	v_add_f32_e32 v48, v48, v49
	v_mul_f32_e32 v49, v60, v60
	v_fmac_f32_e32 v49, v59, v59
	v_add_f32_e32 v48, v48, v49
	v_add_f32_e32 v48, v56, v48
	ds_bpermute_b32 v49, v114, v48
	global_store_dwordx4 v[214:215], v[52:55], off offset:256
	s_waitcnt lgkmcnt(0)
	v_add_f32_e32 v48, v48, v49
	v_mov_b32_e32 v49, v48
	s_nop 1
	v_permlane32_swap_b32_e32 v49, v48
	s_and_saveexec_b64 s[40:41], s[38:39]
	s_cbranch_execz .LBB0_393
	s_waitcnt lgkmcnt(0)
	v_add_f32_e32 v48, v48, v49
	v_fma_f32 v48, v48, s80, 0.5
	v_trunc_f32_e32 v48, v48
	v_mul_f32_e32 v49, 0x2f800000, v48
	v_floor_f32_e32 v49, v49
	v_fmac_f32_e32 v48, 0xcf800000, v49
	v_cvt_u32_f32_e32 v48, v48
	v_cvt_u32_f32_e32 v49, v49
	global_atomic_add_x2 v[112:113], v[48:49], off offset:1024
; #define PG8_GAS __attribute__((address_space(1)))
; __device__ __forceinline__ unsigned cvt_pk_bf16(float lo, float hi) { unsigned r; asm volatile("v_cvt_pk_bf16_f32 %0, %1, %2" : "=v"(r) : "v"(lo), "v"(hi)); return r; }
;     __device__ __forceinline__ void operator()(const f32x4 (&acc)[2][2][4][2], const Unit& u, int wr, int wc, int fr, int fq) const {
;     ...
;             for (int m = 0; m < 4; ++m) { const int row = row0 + ai * HALF + m * 16; PG8_GAS bf16_t* rowb = XBg + (size_t)row * ldc + col0;
;                 float sq = 0.f;
; #pragma unroll
;                 for (int bj = 0; bj < 2; ++bj) { const u32x4 o = pre[ai][m][bj]; const f32x4 c0 = acc[ai][bj][m][0], c1 = acc[ai][bj][m][1];
;                     u32x4 w; w.x = cvt_pk_bf16(__uint_as_float(o.x << 16) + c0[0], __uint_as_float(o.x & 0xffff0000u) + c0[1]); w.y = cvt_pk_bf16(__uint_as_float(o.y << 16) + c0[2], __uint_as_float(o.y & 0xffff0000u) + c0[3]);
;                     w.z = cvt_pk_bf16(__uint_as_float(o.z << 16) + c1[0], __uint_as_float(o.z & 0xffff0000u) + c1[1]); w.w = cvt_pk_bf16(__uint_as_float(o.w << 16) + c1[2], __uint_as_float(o.w & 0xffff0000u) + c1[3]);
;                     *(PG8_GAS u32x4*)(rowb + bj * HALF) = w;
;                     const float a0 = __uint_as_float(w.x << 16), a1 = __uint_as_float(w.x & 0xffff0000u), a2 = __uint_as_float(w.y << 16), a3 = __uint_as_float(w.y & 0xffff0000u);
;                     const float b0 = __uint_as_float(w.z << 16), b1 = __uint_as_float(w.z & 0xffff0000u), b2 = __uint_as_float(w.w << 16), b3 = __uint_as_float(w.w & 0xffff0000u);
;                     sq += (a0 * a0 + a1 * a1) + (a2 * a2 + a3 * a3) + (b0 * b0 + b1 * b1) + (b2 * b2 + b3 * b3); }
;                 sq += __shfl_xor(sq, 16); sq += __shfl_xor(sq, 32);
;                 if (fq == 0) __hip_atomic_fetch_add(ssg + row, (unsigned long long)(sq * 1048576.0f + 0.5f), __ATOMIC_RELAXED, __HIP_MEMORY_SCOPE_AGENT); }
.LBB0_393:
	s_or_b64 exec, exec, s[40:41]
	v_lshlrev_b32_e32 v48, 16, v148
	v_add_f32_e32 v44, v44, v48
	v_and_b32_e32 v48, 0xffff0000, v148
	v_add_f32_e32 v45, v45, v48
	v_cvt_pk_bf16_f32 v44, v44, v45
	v_lshlrev_b32_e32 v45, 16, v149
	v_add_f32_e32 v45, v46, v45
	v_and_b32_e32 v46, 0xffff0000, v149
	v_add_f32_e32 v46, v47, v46
	v_cvt_pk_bf16_f32 v45, v45, v46
	v_lshlrev_b32_e32 v46, 16, v150
	v_add_f32_e32 v40, v40, v46
	v_and_b32_e32 v46, 0xffff0000, v150
	v_add_f32_e32 v41, v41, v46
	v_cvt_pk_bf16_f32 v46, v40, v41
	v_and_b32_e32 v41, 0xffff0000, v151
	v_lshlrev_b32_e32 v40, 16, v151
	v_add_f32_e32 v41, v43, v41
	v_add_f32_e32 v40, v42, v40
	v_cvt_pk_bf16_f32 v47, v40, v41
	v_and_b32_e32 v41, 0xffff0000, v44
	v_lshlrev_b32_e32 v40, 16, v44
	v_and_b32_e32 v43, 0xffff0000, v45
	v_mul_f32_e32 v41, v41, v41
	v_lshlrev_b32_e32 v42, 16, v45
	v_fmac_f32_e32 v41, v40, v40
	v_mul_f32_e32 v40, v43, v43
	global_store_dwordx4 v[212:213], v[44:47], off
	v_fmac_f32_e32 v40, v42, v42
	v_add_f32_e32 v40, v41, v40
	v_and_b32_e32 v45, 0xffff0000, v46
	v_lshlrev_b32_e32 v44, 16, v46
	v_mul_f32_e32 v41, v45, v45
	v_lshlrev_b32_e32 v46, 16, v47
	v_and_b32_e32 v47, 0xffff0000, v47
	v_fmac_f32_e32 v41, v44, v44
	v_add_f32_e32 v40, v40, v41
	v_mul_f32_e32 v41, v47, v47
	v_fmac_f32_e32 v41, v46, v46
	v_add_f32_e32 v40, v40, v41
	v_lshlrev_b32_e32 v41, 16, v144
	v_add_f32_e32 v36, v36, v41
	v_and_b32_e32 v41, 0xffff0000, v144
	v_add_f32_e32 v37, v37, v41
	v_cvt_pk_bf16_f32 v36, v36, v37
	v_lshlrev_b32_e32 v37, 16, v145
	v_add_f32_e32 v37, v38, v37
	v_and_b32_e32 v38, 0xffff0000, v145
	v_add_f32_e32 v38, v39, v38
	v_cvt_pk_bf16_f32 v37, v37, v38
	v_lshlrev_b32_e32 v38, 16, v146
	v_add_f32_e32 v32, v32, v38
	v_and_b32_e32 v38, 0xffff0000, v146
	v_add_f32_e32 v33, v33, v38
	v_cvt_pk_bf16_f32 v38, v32, v33
	v_and_b32_e32 v33, 0xffff0000, v147
	v_lshlrev_b32_e32 v32, 16, v147
	v_add_f32_e32 v33, v35, v33
	v_add_f32_e32 v32, v34, v32
	v_cvt_pk_bf16_f32 v39, v32, v33
	v_and_b32_e32 v33, 0xffff0000, v36
	v_lshlrev_b32_e32 v32, 16, v36
	v_and_b32_e32 v35, 0xffff0000, v37
	v_mul_f32_e32 v33, v33, v33
	v_lshlrev_b32_e32 v34, 16, v37
	v_fmac_f32_e32 v33, v32, v32
	v_mul_f32_e32 v32, v35, v35
	v_and_b32_e32 v42, 0xffff0000, v38
	v_fmac_f32_e32 v32, v34, v34
	v_lshlrev_b32_e32 v41, 16, v38
	v_add_f32_e32 v32, v33, v32
	v_mul_f32_e32 v33, v42, v42
	v_and_b32_e32 v44, 0xffff0000, v39
	v_fmac_f32_e32 v33, v41, v41
	v_lshlrev_b32_e32 v43, 16, v39
	v_add_f32_e32 v32, v32, v33
	v_mul_f32_e32 v33, v44, v44
	v_fmac_f32_e32 v33, v43, v43
	v_add_f32_e32 v32, v32, v33
	v_add_f32_e32 v32, v40, v32
	ds_bpermute_b32 v33, v114, v32
	global_store_dwordx4 v[212:213], v[36:39], off offset:256
	s_waitcnt lgkmcnt(0)
	v_add_f32_e32 v32, v32, v33
	v_mov_b32_e32 v33, v32
	s_nop 1
	v_permlane32_swap_b32_e32 v33, v32
	s_and_saveexec_b64 s[40:41], s[38:39]
	s_cbranch_execz .LBB0_395
	s_waitcnt lgkmcnt(0)
	v_add_f32_e32 v32, v32, v33
	v_fma_f32 v32, v32, s80, 0.5
	v_trunc_f32_e32 v32, v32
	v_mul_f32_e32 v33, 0x2f800000, v32
	v_floor_f32_e32 v33, v33
	v_fmac_f32_e32 v32, 0xcf800000, v33
	v_cvt_u32_f32_e32 v32, v32
	v_cvt_u32_f32_e32 v33, v33
	global_atomic_add_x2 v[112:113], v[32:33], off offset:1152
; #define PG8_GAS __attribute__((address_space(1)))
; __device__ __forceinline__ unsigned cvt_pk_bf16(float lo, float hi) { unsigned r; asm volatile("v_cvt_pk_bf16_f32 %0, %1, %2" : "=v"(r) : "v"(lo), "v"(hi)); return r; }
;     __device__ __forceinline__ void operator()(const f32x4 (&acc)[2][2][4][2], const Unit& u, int wr, int wc, int fr, int fq) const {
;     ...
;             for (int m = 0; m < 4; ++m) { const int row = row0 + ai * HALF + m * 16; PG8_GAS bf16_t* rowb = XBg + (size_t)row * ldc + col0;
;                 float sq = 0.f;
; #pragma unroll
;                 for (int bj = 0; bj < 2; ++bj) { const u32x4 o = pre[ai][m][bj]; const f32x4 c0 = acc[ai][bj][m][0], c1 = acc[ai][bj][m][1];
;                     u32x4 w; w.x = cvt_pk_bf16(__uint_as_float(o.x << 16) + c0[0], __uint_as_float(o.x & 0xffff0000u) + c0[1]); w.y = cvt_pk_bf16(__uint_as_float(o.y << 16) + c0[2], __uint_as_float(o.y & 0xffff0000u) + c0[3]);
;                     w.z = cvt_pk_bf16(__uint_as_float(o.z << 16) + c1[0], __uint_as_float(o.z & 0xffff0000u) + c1[1]); w.w = cvt_pk_bf16(__uint_as_float(o.w << 16) + c1[2], __uint_as_float(o.w & 0xffff0000u) + c1[3]);
;                     *(PG8_GAS u32x4*)(rowb + bj * HALF) = w;
;                     const float a0 = __uint_as_float(w.x << 16), a1 = __uint_as_float(w.x & 0xffff0000u), a2 = __uint_as_float(w.y << 16), a3 = __uint_as_float(w.y & 0xffff0000u);
;                     const float b0 = __uint_as_float(w.z << 16), b1 = __uint_as_float(w.z & 0xffff0000u), b2 = __uint_as_float(w.w << 16), b3 = __uint_as_float(w.w & 0xffff0000u);
;                     sq += (a0 * a0 + a1 * a1) + (a2 * a2 + a3 * a3) + (b0 * b0 + b1 * b1) + (b2 * b2 + b3 * b3); }
;                 sq += __shfl_xor(sq, 16); sq += __shfl_xor(sq, 32);
;                 if (fq == 0) __hip_atomic_fetch_add(ssg + row, (unsigned long long)(sq * 1048576.0f + 0.5f), __ATOMIC_RELAXED, __HIP_MEMORY_SCOPE_AGENT); }
.LBB0_395:
	s_or_b64 exec, exec, s[40:41]
	v_lshlrev_b32_e32 v32, 16, v140
	v_add_f32_e32 v28, v28, v32
	v_and_b32_e32 v32, 0xffff0000, v140
	v_add_f32_e32 v29, v29, v32
	v_cvt_pk_bf16_f32 v28, v28, v29
	v_lshlrev_b32_e32 v29, 16, v141
	v_add_f32_e32 v29, v30, v29
	v_and_b32_e32 v30, 0xffff0000, v141
	v_add_f32_e32 v30, v31, v30
	v_cvt_pk_bf16_f32 v29, v29, v30
	v_lshlrev_b32_e32 v30, 16, v142
	v_add_f32_e32 v24, v24, v30
	v_and_b32_e32 v30, 0xffff0000, v142
	v_add_f32_e32 v25, v25, v30
	v_cvt_pk_bf16_f32 v30, v24, v25
	v_and_b32_e32 v25, 0xffff0000, v143
	v_lshlrev_b32_e32 v24, 16, v143
	v_add_f32_e32 v25, v27, v25
	v_add_f32_e32 v24, v26, v24
	v_cvt_pk_bf16_f32 v31, v24, v25
	v_and_b32_e32 v25, 0xffff0000, v28
	v_lshlrev_b32_e32 v24, 16, v28
	v_and_b32_e32 v27, 0xffff0000, v29
	v_mul_f32_e32 v25, v25, v25
	v_lshlrev_b32_e32 v26, 16, v29
	v_fmac_f32_e32 v25, v24, v24
	v_mul_f32_e32 v24, v27, v27
	global_store_dwordx4 v[210:211], v[28:31], off
	v_fmac_f32_e32 v24, v26, v26
	v_add_f32_e32 v24, v25, v24
	v_and_b32_e32 v29, 0xffff0000, v30
	v_lshlrev_b32_e32 v28, 16, v30
	v_mul_f32_e32 v25, v29, v29
	v_lshlrev_b32_e32 v30, 16, v31
	v_and_b32_e32 v31, 0xffff0000, v31
	v_fmac_f32_e32 v25, v28, v28
	v_add_f32_e32 v24, v24, v25
	v_mul_f32_e32 v25, v31, v31
	v_fmac_f32_e32 v25, v30, v30
	v_add_f32_e32 v24, v24, v25
	v_lshlrev_b32_e32 v25, 16, v128
	v_add_f32_e32 v20, v20, v25
	v_and_b32_e32 v25, 0xffff0000, v128
	v_add_f32_e32 v21, v21, v25
	v_cvt_pk_bf16_f32 v20, v20, v21
	v_lshlrev_b32_e32 v21, 16, v129
	v_add_f32_e32 v21, v22, v21
	v_and_b32_e32 v22, 0xffff0000, v129
	v_add_f32_e32 v22, v23, v22
	v_cvt_pk_bf16_f32 v21, v21, v22
	v_lshlrev_b32_e32 v22, 16, v130
	v_add_f32_e32 v16, v16, v22
	v_and_b32_e32 v22, 0xffff0000, v130
	v_add_f32_e32 v17, v17, v22
	v_cvt_pk_bf16_f32 v22, v16, v17
	v_and_b32_e32 v17, 0xffff0000, v131
	v_lshlrev_b32_e32 v16, 16, v131
	v_add_f32_e32 v17, v19, v17
	v_add_f32_e32 v16, v18, v16
	v_cvt_pk_bf16_f32 v23, v16, v17
	v_and_b32_e32 v17, 0xffff0000, v20
	v_lshlrev_b32_e32 v16, 16, v20
	v_and_b32_e32 v19, 0xffff0000, v21
	v_mul_f32_e32 v17, v17, v17
	v_lshlrev_b32_e32 v18, 16, v21
	v_fmac_f32_e32 v17, v16, v16
	v_mul_f32_e32 v16, v19, v19
	v_and_b32_e32 v26, 0xffff0000, v22
	v_fmac_f32_e32 v16, v18, v18
	v_lshlrev_b32_e32 v25, 16, v22
	v_add_f32_e32 v16, v17, v16
	v_mul_f32_e32 v17, v26, v26
	v_and_b32_e32 v28, 0xffff0000, v23
	v_fmac_f32_e32 v17, v25, v25
	v_lshlrev_b32_e32 v27, 16, v23
	v_add_f32_e32 v16, v16, v17
	v_mul_f32_e32 v17, v28, v28
	v_fmac_f32_e32 v17, v27, v27
	v_add_f32_e32 v16, v16, v17
	v_add_f32_e32 v16, v24, v16
	ds_bpermute_b32 v17, v114, v16
	global_store_dwordx4 v[210:211], v[20:23], off offset:256
	s_waitcnt lgkmcnt(0)
	v_add_f32_e32 v16, v16, v17
	v_mov_b32_e32 v17, v16
	s_nop 1
	v_permlane32_swap_b32_e32 v17, v16
	s_and_saveexec_b64 s[40:41], s[38:39]
	s_cbranch_execz .LBB0_397
	s_waitcnt lgkmcnt(0)
	v_add_f32_e32 v16, v16, v17
	v_fma_f32 v16, v16, s80, 0.5
	v_trunc_f32_e32 v16, v16
	v_mul_f32_e32 v17, 0x2f800000, v16
	v_floor_f32_e32 v17, v17
	v_fmac_f32_e32 v16, 0xcf800000, v17
	v_cvt_u32_f32_e32 v16, v16
	v_cvt_u32_f32_e32 v17, v17
	global_atomic_add_x2 v[112:113], v[16:17], off offset:1280
.LBB0_397:
	s_or_b64 exec, exec, s[40:41]
	s_waitcnt vmcnt(15)
	v_lshlrev_b32_e32 v16, 16, v132
	v_add_f32_e32 v12, v12, v16
	v_and_b32_e32 v16, 0xffff0000, v132
	v_add_f32_e32 v13, v13, v16
	v_cvt_pk_bf16_f32 v12, v12, v13
	v_lshlrev_b32_e32 v13, 16, v133
	v_add_f32_e32 v13, v14, v13
	v_and_b32_e32 v14, 0xffff0000, v133
	v_add_f32_e32 v14, v15, v14
	v_cvt_pk_bf16_f32 v13, v13, v14
	v_lshlrev_b32_e32 v14, 16, v134
	v_add_f32_e32 v8, v8, v14
	v_and_b32_e32 v14, 0xffff0000, v134
	v_add_f32_e32 v9, v9, v14
	v_cvt_pk_bf16_f32 v14, v8, v9
	v_and_b32_e32 v9, 0xffff0000, v135
	v_lshlrev_b32_e32 v8, 16, v135
	v_add_f32_e32 v9, v11, v9
	v_add_f32_e32 v8, v10, v8
	v_cvt_pk_bf16_f32 v15, v8, v9
	v_and_b32_e32 v9, 0xffff0000, v12
	v_lshlrev_b32_e32 v8, 16, v12
	v_and_b32_e32 v11, 0xffff0000, v13
	v_mul_f32_e32 v9, v9, v9
	v_lshlrev_b32_e32 v10, 16, v13
	v_fmac_f32_e32 v9, v8, v8
	v_mul_f32_e32 v8, v11, v11
	global_store_dwordx4 v[208:209], v[12:15], off
	v_fmac_f32_e32 v8, v10, v10
	v_add_f32_e32 v8, v9, v8
	v_and_b32_e32 v13, 0xffff0000, v14
	v_lshlrev_b32_e32 v12, 16, v14
	v_mul_f32_e32 v9, v13, v13
	v_lshlrev_b32_e32 v14, 16, v15
	v_and_b32_e32 v15, 0xffff0000, v15
	v_fmac_f32_e32 v9, v12, v12
	v_add_f32_e32 v8, v8, v9
	v_mul_f32_e32 v9, v15, v15
	v_fmac_f32_e32 v9, v14, v14
	v_add_f32_e32 v8, v8, v9
	s_waitcnt vmcnt(15)
	v_lshlrev_b32_e32 v9, 16, v124
	v_add_f32_e32 v4, v4, v9
	v_and_b32_e32 v9, 0xffff0000, v124
	v_add_f32_e32 v5, v5, v9
	v_cvt_pk_bf16_f32 v4, v4, v5
	v_lshlrev_b32_e32 v5, 16, v125
	v_add_f32_e32 v5, v6, v5
	v_and_b32_e32 v6, 0xffff0000, v125
	v_add_f32_e32 v6, v7, v6
	v_cvt_pk_bf16_f32 v5, v5, v6
	v_lshlrev_b32_e32 v6, 16, v126
	v_add_f32_e32 v0, v0, v6
	v_and_b32_e32 v6, 0xffff0000, v126
	v_add_f32_e32 v1, v1, v6
	v_cvt_pk_bf16_f32 v6, v0, v1
	v_and_b32_e32 v1, 0xffff0000, v127
	v_lshlrev_b32_e32 v0, 16, v127
	v_add_f32_e32 v1, v3, v1
	v_add_f32_e32 v0, v2, v0
	v_cvt_pk_bf16_f32 v7, v0, v1
	v_and_b32_e32 v1, 0xffff0000, v4
	v_lshlrev_b32_e32 v0, 16, v4
	v_and_b32_e32 v3, 0xffff0000, v5
	v_mul_f32_e32 v1, v1, v1
	v_lshlrev_b32_e32 v2, 16, v5
	v_fmac_f32_e32 v1, v0, v0
	v_mul_f32_e32 v0, v3, v3
	v_and_b32_e32 v10, 0xffff0000, v6
	v_fmac_f32_e32 v0, v2, v2
	v_lshlrev_b32_e32 v9, 16, v6
	v_add_f32_e32 v0, v1, v0
	v_mul_f32_e32 v1, v10, v10
	v_and_b32_e32 v12, 0xffff0000, v7
	v_fmac_f32_e32 v1, v9, v9
	v_lshlrev_b32_e32 v11, 16, v7
	v_add_f32_e32 v0, v0, v1
	v_mul_f32_e32 v1, v12, v12
	v_fmac_f32_e32 v1, v11, v11
	v_add_f32_e32 v0, v0, v1
	v_add_f32_e32 v0, v8, v0
	ds_bpermute_b32 v1, v114, v0
	global_store_dwordx4 v[208:209], v[4:7], off offset:256
	s_waitcnt lgkmcnt(0)
	v_add_f32_e32 v0, v0, v1
	v_mov_b32_e32 v1, v0
	s_nop 1
	v_permlane32_swap_b32_e32 v1, v0
	s_and_saveexec_b64 s[40:41], s[38:39]
	s_cbranch_execz .LBB0_399
	s_waitcnt lgkmcnt(0)
	v_add_f32_e32 v0, v0, v1
	v_fma_f32 v0, v0, s80, 0.5
	v_trunc_f32_e32 v0, v0
	v_mul_f32_e32 v1, 0x2f800000, v0
	v_floor_f32_e32 v1, v1
	v_fmac_f32_e32 v0, 0xcf800000, v1
	v_cvt_u32_f32_e32 v0, v0
	v_cvt_u32_f32_e32 v1, v1
	global_atomic_add_x2 v[112:113], v[0:1], off offset:1408
